# P9 epilogue: nt (non-temporal) hint on the streaming residual loads and output stores, on p0map
# baseline (speedup 1.0000x reference)
.LBB0_1022:
	s_ashr_i32 s23, s30, 5
	v_lshl_or_b32 v0, s55, 8, v182
	s_mul_hi_i32 s25, s23, 0x18000
	s_mul_i32 s23, s23, 0x18000
	s_add_u32 s36, s48, s23
	v_ashrrev_i32_e32 v1, 31, v0
	s_addc_u32 s37, s49, s25
	v_lshlrev_b64 v[0:1], 2, v[0:1]
	v_lshl_add_u64 v[10:11], s[36:37], 0, v[0:1]
	global_load_dwordx4 v[2:5], v[10:11], off nt
	global_load_dwordx4 v[6:9], v[10:11], off offset:64 nt
	global_load_dwordx4 v[22:25], v[10:11], off offset:512 nt
	global_load_dwordx4 v[26:29], v[10:11], off offset:576 nt
	v_lshl_add_u32 v10, s30, 8, v180
	v_ashrrev_i32_e32 v11, 31, v10
	v_lshl_add_u64 v[18:19], s[4:5], 0, v[0:1]
	v_lshlrev_b64 v[20:21], 14, v[10:11]
	v_lshl_add_u64 v[12:13], v[18:19], 0, v[20:21]
	global_load_dwordx4 v[172:175], v[12:13], off nt
	global_load_dwordx4 v[176:179], v[12:13], off offset:64 nt
	global_load_dwordx4 v[188:191], v[12:13], off offset:512 nt
	global_load_dwordx4 v[192:195], v[12:13], off offset:576 nt
	v_or_b32_e32 v12, 16, v10
	v_ashrrev_i32_e32 v13, 31, v12
	v_lshlrev_b64 v[12:13], 14, v[12:13]
	v_lshl_add_u64 v[14:15], v[18:19], 0, v[12:13]
	global_load_dwordx4 v[196:199], v[14:15], off nt
	global_load_dwordx4 v[200:203], v[14:15], off offset:64 nt
	global_load_dwordx4 v[204:207], v[14:15], off offset:512 nt
	global_load_dwordx4 v[208:211], v[14:15], off offset:576 nt
	v_or_b32_e32 v14, 32, v10
	v_ashrrev_i32_e32 v15, 31, v14
	v_lshlrev_b64 v[14:15], 14, v[14:15]
	v_lshl_add_u64 v[16:17], v[18:19], 0, v[14:15]
	global_load_dwordx4 v[212:215], v[16:17], off nt
	global_load_dwordx4 v[216:219], v[16:17], off offset:64 nt
	global_load_dwordx4 v[220:223], v[16:17], off offset:512 nt
	v_or_b32_e32 v10, 48, v10
	global_load_dwordx4 v[224:227], v[16:17], off offset:576 nt
	v_ashrrev_i32_e32 v11, 31, v10
	v_lshlrev_b64 v[244:245], 14, v[10:11]
	v_lshl_add_u64 v[10:11], v[18:19], 0, v[244:245]
	global_load_dwordx4 v[228:231], v[10:11], off nt
	global_load_dwordx4 v[232:235], v[10:11], off offset:64 nt
	global_load_dwordx4 v[236:239], v[10:11], off offset:512 nt
	global_load_dwordx4 v[240:243], v[10:11], off offset:576 nt
	v_lshl_add_u64 v[10:11], s[4:5], 0, v[20:21]
	v_lshl_add_u64 v[246:247], v[10:11], 0, v[0:1]
	v_lshl_add_u64 v[10:11], s[4:5], 0, v[12:13]
	v_lshl_add_u64 v[12:13], s[4:5], 0, v[14:15]
	v_lshl_add_u64 v[248:249], v[10:11], 0, v[0:1]
	v_lshl_add_u64 v[250:251], v[12:13], 0, v[0:1]
	s_andn2_b64 vcc, exec, s[0:1]
	s_mov_b64 s[0:1], -1
	s_waitcnt vmcnt(0)
	v_pk_mul_f32 v[14:15], v[4:5], s[14:15] op_sel_hi:[1,0]
	v_pk_mul_f32 v[16:17], v[2:3], s[14:15] op_sel_hi:[1,0]
	v_pk_mul_f32 v[10:11], v[8:9], s[14:15] op_sel_hi:[1,0]
	v_pk_mul_f32 v[12:13], v[6:7], s[14:15] op_sel_hi:[1,0]
	v_pk_mul_f32 v[6:7], v[24:25], s[14:15] op_sel_hi:[1,0]
	v_pk_mul_f32 v[8:9], v[22:23], s[14:15] op_sel_hi:[1,0]
	v_pk_mul_f32 v[2:3], v[28:29], s[14:15] op_sel_hi:[1,0]
	v_pk_mul_f32 v[4:5], v[26:27], s[14:15] op_sel_hi:[1,0]
	v_pk_fma_f32 v[24:25], v[158:159], v[14:15], v[174:175]
	v_pk_fma_f32 v[22:23], v[156:157], v[16:17], v[172:173]
	v_pk_fma_f32 v[28:29], v[154:155], v[10:11], v[178:179]
	v_pk_fma_f32 v[26:27], v[152:153], v[12:13], v[176:177]
	v_pk_fma_f32 v[138:139], v[138:139], v[6:7], v[190:191]
	v_pk_fma_f32 v[136:137], v[136:137], v[8:9], v[188:189]
	v_pk_fma_f32 v[134:135], v[134:135], v[2:3], v[194:195]
	v_pk_fma_f32 v[132:133], v[132:133], v[4:5], v[192:193]
	v_pk_fma_f32 v[150:151], v[150:151], v[14:15], v[198:199]
	v_pk_fma_f32 v[148:149], v[148:149], v[16:17], v[196:197]
	v_pk_fma_f32 v[146:147], v[146:147], v[10:11], v[202:203]
	v_pk_fma_f32 v[144:145], v[144:145], v[12:13], v[200:201]
	v_pk_fma_f32 v[130:131], v[130:131], v[6:7], v[206:207]
	v_pk_fma_f32 v[128:129], v[128:129], v[8:9], v[204:205]
	v_pk_fma_f32 v[122:123], v[122:123], v[2:3], v[210:211]
	v_pk_fma_f32 v[120:121], v[120:121], v[4:5], v[208:209]
	v_pk_fma_f32 v[142:143], v[142:143], v[14:15], v[214:215]
	v_pk_fma_f32 v[140:141], v[140:141], v[16:17], v[212:213]
	global_store_dwordx4 v[246:247], v[22:25], off nt
	global_store_dwordx4 v[246:247], v[26:29], off offset:64 nt
	global_store_dwordx4 v[246:247], v[136:139], off offset:512 nt
	global_store_dwordx4 v[246:247], v[132:135], off offset:576 nt
	global_store_dwordx4 v[248:249], v[148:151], off nt
	global_store_dwordx4 v[248:249], v[144:147], off offset:64 nt
	global_store_dwordx4 v[248:249], v[128:131], off offset:512 nt
	global_store_dwordx4 v[248:249], v[120:123], off offset:576 nt
	global_store_dwordx4 v[250:251], v[140:143], off nt
	v_pk_fma_f32 v[24:25], v[114:115], v[6:7], v[222:223]
	v_pk_fma_f32 v[22:23], v[112:113], v[8:9], v[220:221]
	global_store_dwordx4 v[250:251], v[22:25], off offset:512 nt
	v_lshl_add_u64 v[26:27], s[4:5], 0, v[244:245]
	v_lshl_add_u64 v[26:27], v[26:27], 0, v[0:1]
	v_pk_fma_f32 v[24:25], v[106:107], v[2:3], v[226:227]
	v_pk_fma_f32 v[22:23], v[104:105], v[4:5], v[224:225]
	global_store_dwordx4 v[250:251], v[22:25], off offset:576 nt
	v_pk_fma_f32 v[30:31], v[126:127], v[10:11], v[218:219]
	v_pk_fma_f32 v[28:29], v[124:125], v[12:13], v[216:217]
	v_pk_fma_f32 v[24:25], v[118:119], v[14:15], v[230:231]
	v_pk_fma_f32 v[22:23], v[116:117], v[16:17], v[228:229]
	global_store_dwordx4 v[26:27], v[22:25], off nt
	global_store_dwordx4 v[250:251], v[28:31], off offset:64 nt
	v_lshl_add_u64 v[148:149], v[20:21], 0, s[16:17]
	v_pk_fma_f32 v[24:25], v[110:111], v[10:11], v[234:235]
	v_pk_fma_f32 v[22:23], v[108:109], v[12:13], v[232:233]
	global_store_dwordx4 v[26:27], v[22:25], off offset:64 nt
	v_lshl_add_u64 v[30:31], v[20:21], 0, s[8:9]
	v_lshl_add_u64 v[104:105], v[18:19], 0, v[30:31]
	v_pk_fma_f32 v[24:25], v[102:103], v[6:7], v[238:239]
	v_pk_fma_f32 v[22:23], v[100:101], v[8:9], v[236:237]
	global_store_dwordx4 v[26:27], v[22:25], off offset:512 nt
	v_lshl_add_u64 v[116:117], v[18:19], 0, v[148:149]
	v_lshl_add_u64 v[150:151], v[20:21], 0, s[18:19]
	v_pk_fma_f32 v[24:25], v[98:99], v[2:3], v[242:243]
	v_pk_fma_f32 v[22:23], v[96:97], v[4:5], v[240:241]
	global_store_dwordx4 v[26:27], v[22:25], off offset:576 nt
	v_lshl_add_u64 v[152:153], v[20:21], 0, s[20:21]
	global_load_dwordx4 v[22:25], v[104:105], off nt
	global_load_dwordx4 v[26:29], v[104:105], off offset:64 nt
	global_load_dwordx4 v[96:99], v[104:105], off offset:512 nt
	global_load_dwordx4 v[100:103], v[104:105], off offset:576 nt
	s_nop 0
	global_load_dwordx4 v[104:107], v[116:117], off nt
	global_load_dwordx4 v[108:111], v[116:117], off offset:64 nt
	global_load_dwordx4 v[112:115], v[116:117], off offset:512 nt
	s_nop 0
	global_load_dwordx4 v[116:119], v[116:117], off offset:576 nt
	v_lshl_add_u64 v[132:133], v[18:19], 0, v[150:151]
	v_lshl_add_u64 v[144:145], v[18:19], 0, v[152:153]
	global_load_dwordx4 v[120:123], v[132:133], off nt
	global_load_dwordx4 v[124:127], v[132:133], off offset:64 nt
	global_load_dwordx4 v[128:131], v[132:133], off offset:512 nt
	s_nop 0
	global_load_dwordx4 v[132:135], v[132:133], off offset:576 nt
	s_nop 0
	global_load_dwordx4 v[18:21], v[144:145], off nt
	global_load_dwordx4 v[136:139], v[144:145], off offset:64 nt
	global_load_dwordx4 v[140:143], v[144:145], off offset:512 nt
	s_nop 0
	global_load_dwordx4 v[144:147], v[144:145], off offset:576 nt
	v_lshl_add_u64 v[30:31], s[4:5], 0, v[30:31]
	v_lshl_add_u64 v[148:149], s[4:5], 0, v[148:149]
	v_lshl_add_u64 v[150:151], s[4:5], 0, v[150:151]
	v_lshl_add_u64 v[30:31], v[30:31], 0, v[0:1]
	v_lshl_add_u64 v[148:149], v[148:149], 0, v[0:1]
	v_lshl_add_u64 v[150:151], v[150:151], 0, v[0:1]
	s_waitcnt vmcnt(15)
	v_pk_fma_f32 v[24:25], v[94:95], v[14:15], v[24:25]
	v_pk_fma_f32 v[22:23], v[92:93], v[16:17], v[22:23]
	s_waitcnt vmcnt(14)
	v_pk_fma_f32 v[28:29], v[90:91], v[10:11], v[28:29]
	v_pk_fma_f32 v[26:27], v[88:89], v[12:13], v[26:27]
	s_waitcnt vmcnt(13)
	v_pk_fma_f32 v[74:75], v[74:75], v[6:7], v[98:99]
	v_pk_fma_f32 v[72:73], v[72:73], v[8:9], v[96:97]
	s_waitcnt vmcnt(12)
	v_pk_fma_f32 v[70:71], v[70:71], v[2:3], v[102:103]
	v_pk_fma_f32 v[68:69], v[68:69], v[4:5], v[100:101]
	s_waitcnt vmcnt(11)
	v_pk_fma_f32 v[86:87], v[86:87], v[14:15], v[106:107]
	v_pk_fma_f32 v[84:85], v[84:85], v[16:17], v[104:105]
	s_waitcnt vmcnt(10)
	v_pk_fma_f32 v[82:83], v[82:83], v[10:11], v[110:111]
	v_pk_fma_f32 v[80:81], v[80:81], v[12:13], v[108:109]
	s_waitcnt vmcnt(9)
	v_pk_fma_f32 v[62:63], v[62:63], v[6:7], v[114:115]
	v_pk_fma_f32 v[60:61], v[60:61], v[8:9], v[112:113]
	s_waitcnt vmcnt(8)
	v_pk_fma_f32 v[58:59], v[58:59], v[2:3], v[118:119]
	v_pk_fma_f32 v[56:57], v[56:57], v[4:5], v[116:117]
	s_waitcnt vmcnt(7)
	v_pk_fma_f32 v[78:79], v[78:79], v[14:15], v[122:123]
	v_pk_fma_f32 v[76:77], v[76:77], v[16:17], v[120:121]
	s_waitcnt vmcnt(6)
	v_pk_fma_f32 v[66:67], v[66:67], v[10:11], v[126:127]
	v_pk_fma_f32 v[64:65], v[64:65], v[12:13], v[124:125]
	global_store_dwordx4 v[30:31], v[22:25], off nt
	global_store_dwordx4 v[30:31], v[26:29], off offset:64 nt
	global_store_dwordx4 v[30:31], v[72:75], off offset:512 nt
	global_store_dwordx4 v[30:31], v[68:71], off offset:576 nt
	global_store_dwordx4 v[148:149], v[84:87], off nt
	global_store_dwordx4 v[148:149], v[80:83], off offset:64 nt
	global_store_dwordx4 v[148:149], v[60:63], off offset:512 nt
	global_store_dwordx4 v[148:149], v[56:59], off offset:576 nt
	global_store_dwordx4 v[150:151], v[76:79], off nt
	global_store_dwordx4 v[150:151], v[64:67], off offset:64 nt
	s_waitcnt vmcnt(15)
	v_pk_fma_f32 v[24:25], v[50:51], v[6:7], v[130:131]
	v_pk_fma_f32 v[22:23], v[48:49], v[8:9], v[128:129]
	s_waitcnt vmcnt(13)
	v_pk_fma_f32 v[20:21], v[54:55], v[14:15], v[20:21]
	v_lshl_add_u64 v[14:15], s[4:5], 0, v[152:153]
	global_store_dwordx4 v[150:151], v[22:25], off offset:512 nt
	v_pk_fma_f32 v[18:19], v[52:53], v[16:17], v[18:19]
	v_lshl_add_u64 v[16:17], v[14:15], 0, v[0:1]
	v_pk_fma_f32 v[24:25], v[42:43], v[2:3], v[134:135]
	v_pk_fma_f32 v[22:23], v[40:41], v[4:5], v[132:133]
	s_waitcnt vmcnt(13)
	v_pk_fma_f32 v[14:15], v[46:47], v[10:11], v[138:139]
	v_pk_fma_f32 v[12:13], v[44:45], v[12:13], v[136:137]
	s_waitcnt vmcnt(12)
	v_pk_fma_f32 v[10:11], v[38:39], v[6:7], v[142:143]
	v_pk_fma_f32 v[8:9], v[36:37], v[8:9], v[140:141]
	s_waitcnt vmcnt(11)
	v_pk_fma_f32 v[2:3], v[34:35], v[2:3], v[146:147]
	v_pk_fma_f32 v[0:1], v[32:33], v[4:5], v[144:145]
	global_store_dwordx4 v[150:151], v[22:25], off offset:576 nt
	global_store_dwordx4 v[16:17], v[18:21], off nt
	global_store_dwordx4 v[16:17], v[12:15], off offset:64 nt
	global_store_dwordx4 v[16:17], v[8:11], off offset:512 nt
	global_store_dwordx4 v[16:17], v[0:3], off offset:576 nt
	s_cbranch_vccnz .LBB0_1011
	s_nop 7
	s_andn2_b64 vcc, exec, s[10:11]
	s_cbranch_vccnz .LBB0_1010
	s_barrier
	s_branch .LBB0_1010
